# m2 phase: rotate the vt-item work assignment by 96 workgroups so the workgroups with a second vt round are not the ones that also have a third gmlp/ssd item
# speedup vs baseline: 1.0095x; 1.0095x over previous
.LBB0_443:
	s_or_b64 exec, exec, s[4:5]
	s_ashr_i32 s39, s73, 31
	s_lshr_b32 s2, s39, 29
	s_add_i32 s2, s73, s2
	s_ashr_i32 s10, s2, 3
	s_and_b32 s2, s2, -8
	s_sub_i32 s11, s73, s2
	s_ashr_i32 s2, s3, 31
	v_writelane_b32 v243, s2, 6
	s_lshl_b32 s2, s73, 6
	s_and_b32 s2, s2, 0x1c0
	v_writelane_b32 v243, s2, 7
	s_lshr_b32 s2, s3, 3
	s_cmp_gt_i32 s73, 31
	v_writelane_b32 v243, s2, 8
	s_cselect_b64 s[4:5], -1, 0
	s_sub_i32 s2, s73, 32
	v_writelane_b32 v243, s4, 9
	s_cmpk_lt_u32 s73, 0x220
	s_mov_b32 s49, 0
	v_writelane_b32 v243, s5, 10
	s_cselect_b64 s[4:5], -1, 0
	v_writelane_b32 v243, s4, 11
	s_mov_b32 s13, s49
	v_mbcnt_lo_u32_b32 v3, -1, 0
	v_writelane_b32 v243, s5, 12
	s_sub_i32 s4, s3, 32
	v_writelane_b32 v243, s4, 13
	v_writelane_b32 v243, s2, 14
	s_sub_i32 s2, s73, 0x80
	s_cmp_lt_i32 s2, 0
	s_cselect_b32 s4, 0xe0, 0
	s_add_i32 s2, s2, s4
	s_lshl_b32 s2, s2, 3
	v_writelane_b32 v243, s2, 15
	s_add_i32 s2, s76, 0xffffff00
	v_writelane_b32 v243, s2, 16
	s_lshl_b32 s2, s11, 2
	s_lshl_b32 s4, s3, 9
	s_cmpk_lg_i32 s3, 0x100
	v_writelane_b32 v243, s4, 17
	s_cselect_b64 s[4:5], -1, 0
	v_writelane_b32 v243, s4, 18
	s_cmpk_lt_i32 s73, 0x200
	s_movk_i32 s79, 0xff00
	v_writelane_b32 v243, s5, 19
	s_cselect_b64 s[4:5], -1, 0
	v_writelane_b32 v243, s4, 20
	s_bfe_u32 s6, s73, 0x10001
	s_lshl_b32 s8, s6, 11
	v_writelane_b32 v243, s5, 21
	s_lshl_b32 s4, s73, 5
	v_writelane_b32 v243, s4, 22
	s_and_b32 s4, s4, 32
	s_add_i32 s87, s8, 0
	s_lshr_b32 s8, s73, 3
	s_add_i32 s4, s4, s8
	s_lshl_b32 s4, s4, 7
	v_writelane_b32 v243, s4, 23
	s_lshl_b32 s4, s6, 2
	s_bfe_u32 s5, s73, 0x10002
	v_writelane_b32 v243, s4, 24
	s_or_b32 s4, s4, 1
	s_lshl_b32 s7, s5, 1
	s_lshl_b32 s12, s5, 14
	s_lshl_b32 s5, s6, 8
	s_lshl_b32 s9, s4, 6
	v_writelane_b32 v243, s9, 25
	s_or_b32 s9, s5, 0x80
	v_writelane_b32 v243, s9, 26
	s_or_b32 s7, s7, s6
	v_writelane_b32 v243, s5, 27
	s_or_b32 s5, s5, 0xc0
	s_add_i32 s87, s87, 0x24000
	v_writelane_b32 v243, s5, 28
	s_lshl_b32 s5, s7, 20
	s_cmpk_lt_i32 s73, 0x100
	v_writelane_b32 v243, s5, 29
	s_cselect_b64 s[14:15], -1, 0
	v_writelane_b32 v243, s14, 30
	s_lshl_b32 s5, s11, 6
	s_mul_i32 s6, s6, 12
	v_writelane_b32 v243, s15, 31
	v_writelane_b32 v243, s12, 32
	s_lshl_b32 s14, s3, 4
	s_lshl_b32 s15, s7, 17
	v_writelane_b32 v243, s13, 33
	s_cmp_lt_i32 s11, 0
	s_mul_i32 s7, s11, 5
	v_writelane_b32 v243, s6, 34
	s_mul_i32 s4, s4, 3
	v_writelane_b32 v243, s4, 35
	s_mul_i32 s4, s11, 0x41
	s_cselect_b32 s2, s7, s2
	s_cselect_b32 s9, s4, s5
	s_add_i32 s7, s2, s10
	s_ashr_i32 s2, s7, 31
	s_lshr_b32 s4, s2, 29
	s_add_i32 s6, s7, s4
	s_ashr_i32 s4, s6, 3
	s_and_b32 s6, s6, 0x1f8
	s_sub_i32 s6, s7, s6
	s_mul_i32 s6, s6, 0x1800000
	s_lshr_b32 s2, s2, 28
	v_writelane_b32 v243, s6, 36
	s_ashr_i32 s6, s6, 31
	s_add_i32 s2, s7, s2
	v_writelane_b32 v243, s6, 37
	s_ashr_i32 s6, s2, 4
	v_writelane_b32 v243, s7, 38
	s_ashr_i32 s7, s6, 31
	s_lshl_b64 s[6:7], s[6:7], 20
	s_ashr_i32 s5, s4, 31
	v_writelane_b32 v243, s6, 39
	s_lshl_b64 s[4:5], s[4:5], 7
	s_add_i32 s2, s9, s10
	v_writelane_b32 v243, s7, 40
	v_writelane_b32 v243, s4, 41
	s_mov_b32 s38, 2
	s_movk_i32 s85, 0x200
	v_writelane_b32 v243, s5, 42
	s_ashr_i32 s4, s2, 31
	s_lshr_b32 s4, s4, 27
	s_add_i32 s4, s2, s4
	s_ashr_i32 s5, s4, 5
	s_and_b32 s4, s4, 0xffe0
	s_sub_i32 s4, s2, s4
	s_bfe_i32 s2, s4, 0x80000
	s_bfe_u32 s2, s2, 0x3000c
	s_add_i32 s6, s4, s2
	s_bfe_i32 s2, s6, 0x80000
	s_and_b32 s6, s6, 0xf8
	s_sub_i32 s4, s4, s6
	s_lshl_b32 s5, s5, 3
	s_sext_i32_i8 s4, s4
	v_writelane_b32 v243, s10, 43
	s_sext_i32_i16 s7, s2
	s_add_i32 s4, s5, s4
	s_lshr_b32 s2, s7, 3
	v_writelane_b32 v243, s4, 44
	s_ashr_i32 s4, s7, 3
	v_writelane_b32 v243, s4, 45
	s_bfe_i64 s[4:5], s[2:3], 0x100000
	v_writelane_b32 v243, s4, 46
	s_lshr_b32 s2, s11, 31
	v_mov_b32_e32 v11, 0
	v_writelane_b32 v243, s5, 47
	v_writelane_b32 v243, s11, 48
	v_writelane_b32 v243, s2, 49
	s_add_i32 s2, s73, 0xfffffee0
	v_writelane_b32 v243, s2, 50
	s_lshl_b32 s2, s73, 7
	v_writelane_b32 v243, s2, 51
	s_addk_i32 s2, 0xf000
	v_writelane_b32 v243, s2, 52
	s_lshl_b32 s2, s3, 7
	v_writelane_b32 v243, s2, 53
	s_addk_i32 s2, 0xf000
	v_writelane_b32 v243, s2, 54
	s_lshl_b32 s2, s3, 5
	s_bitcmp1_b32 s73, 0
	v_writelane_b32 v243, s2, 55
	s_cselect_b64 s[4:5], -1, 0
	v_writelane_b32 v243, s4, 56
	s_and_b32 s2, s73, 1
	s_lshl_b32 s2, s2, 12
	v_writelane_b32 v243, s5, 57
	s_lshl_b32 s4, s8, 7
	s_add_i32 s2, s2, s4
	s_add_i32 s4, s2, 0xfffffbf1
	v_writelane_b32 v243, s4, 58
	v_writelane_b32 v243, s15, 59
	s_or_b32 s4, s15, 0x15c80c00
	v_writelane_b32 v243, s4, 60
	s_or_b32 s4, s2, 15
	v_writelane_b32 v243, s4, 61
	s_sub_i32 s4, 0x3b71, s2
	s_sub_i32 s2, 0x3f8f, s2
	s_bitcmp1_b32 s3, 0
	v_writelane_b32 v243, s4, 62
	s_cselect_b64 s[4:5], -1, 0
	v_writelane_b32 v242, s4, 0
	v_writelane_b32 v243, s2, 63
	s_add_i32 s2, 0, 0x20400
	v_writelane_b32 v242, s5, 1
	v_writelane_b32 v242, s2, 2
	s_add_i32 s2, 0, 0x20c00
	v_writelane_b32 v242, s2, 3
	s_add_i32 s2, 0, 0x21800
	v_writelane_b32 v242, s2, 4
	s_add_i32 s2, 0, 0x22000
	v_writelane_b32 v242, s2, 5
	s_add_i32 s2, 0, 0x23000
	v_writelane_b32 v242, s2, 6
	s_add_i32 s2, 0, 0x11000
	v_writelane_b32 v242, s2, 7
	s_add_i32 s2, 0, 0x11008
	v_writelane_b32 v242, s2, 8
	v_cmp_ne_u32_e64 s[4:5], 0, v2
	s_mov_b32 s2, s14
	s_mov_b64 s[8:9], 0
	v_writelane_b32 v242, s4, 9
	s_ashr_i32 s15, s14, 31
	v_mov_b32_e32 v175, 0xe0000
	v_writelane_b32 v242, s5, 10
	v_writelane_b32 v242, s2, 11
	v_mov_b32_e32 v202, 0xe1000
	v_mov_b32_e32 v203, 0xffff
	v_writelane_b32 v242, s3, 12
	v_writelane_b32 v242, s8, 13
	s_mov_b32 s2, s76
	v_mov_b32_e32 v174, 0x3727c5ac
	v_writelane_b32 v242, s9, 14
	v_mov_b32_e32 v204, 1
	v_mov_b32_e32 v205, 0x7f800000
	v_mov_b32_e32 v206, 0x7fc00000
	v_mov_b32_e32 v207, 0xff800000
	v_mbcnt_hi_u32_b32 v208, -1, v3
	v_mov_b32_e32 v209, 0x1e000
	v_mov_b32_e32 v210, 0x24000
	v_mov_b32_e32 v211, 0x2a000
	v_mov_b32_e32 v212, 0x1800
	v_mov_b32_e32 v213, 0x60
	v_mov_b64_e32 v[176:177], 0x200
	v_mov_b64_e32 v[178:179], 0x1ff
	s_movk_i32 s33, 0x300
	s_movk_i32 s37, 0x1600
	s_movk_i32 s83, 0x60
	s_mov_b32 s89, 0xff800000
	s_movk_i32 s64, 0x1800
	s_movk_i32 s65, 0xffe0
	s_movk_i32 s42, 0xff
	s_mov_b32 s43, 0x5040100
	s_mov_b32 s52, 0x800000
	s_movk_i32 s53, 0x7f
	s_movk_i32 s36, 0xfbf
	s_mov_b32 s80, 0xfff80000
	s_movk_i32 s84, 0xfb
	s_movk_i32 s81, 0x108
	s_add_i32 s82, 0, 0x22800
	s_movk_i32 s78, 0xdf
	s_mov_b32 s7, 0
	s_lshl_b64 s[66:67], s[14:15], 12
	s_lshl_b64 s[68:69], s[14:15], 11
	s_mov_b64 s[4:5], -1
	s_mov_b64 s[74:75], 0x80
	s_mov_b32 s86, 0x3e000000
	s_mov_b32 s88, 0x3fb8aa3b
	s_mov_b64 s[94:95], 0x18000
	s_mov_b64 s[44:45], 0x80000
	s_mov_b64 s[56:57], 0x800
	s_mov_b64 s[58:59], 0x1000
	s_mov_b64 s[60:61], 0x30000
	s_mov_b32 s72, 0x3fb504f3
	v_writelane_b32 v242, s2, 15
	s_barrier
	s_nop 0
	v_writelane_b32 v242, s3, 16
	s_branch .LBB0_445
